# also the grid barrier after glu replaced by the panel-group sync (write-through glu output)
# speedup vs baseline: 1.0370x; 1.0085x over previous
.LBB0_671:
	v_mul_f32_e32 v124, 0xbfb8aa3b, v124
	v_mul_f32_e32 v125, 0xbfb8aa3b, v125
	v_exp_f32_e32 v124, v124
	v_exp_f32_e32 v125, v125
	v_mul_f32_e32 v116, 0xbfb8aa3b, v116
	v_mul_f32_e32 v117, 0xbfb8aa3b, v117
	v_exp_f32_e32 v116, v116
	v_pk_add_f32 v[124:125], v[124:125], 1.0 op_sel_hi:[1,0]
	v_exp_f32_e32 v117, v117
	s_nop 0
	v_pk_add_f32 v[116:117], v[116:117], 1.0 op_sel_hi:[1,0]
	v_mul_f32_e32 v108, 0xbfb8aa3b, v108
	v_mul_f32_e32 v109, 0xbfb8aa3b, v109
	v_rcp_f32_e32 v128, v125
	s_nop 0
	v_mul_f32_e32 v125, 1.0, v128
	s_lshl_b32 s4, s4, 7
	v_exp_f32_e32 v108, v108
	v_exp_f32_e32 v109, v109
	v_rcp_f32_e32 v128, v124
	s_nop 0
	v_mul_f32_e32 v124, 1.0, v128
	v_pk_mul_f32 v[120:121], v[120:121], v[124:125]
	v_mul_f32_e32 v124, 0xbfb8aa3b, v126
	v_mul_f32_e32 v125, 0xbfb8aa3b, v127
	v_exp_f32_e32 v124, v124
	v_exp_f32_e32 v125, v125
	v_cvt_pk_bf16_f32 v120, v120, v121
	s_ashr_i32 s5, s4, 31
	s_lshl_b64 s[4:5], s[4:5], 1
	v_pk_add_f32 v[124:125], v[124:125], 1.0 op_sel_hi:[1,0]
	s_lshl_b32 s84, s28, 1
	v_pk_add_f32 v[108:109], v[108:109], 1.0 op_sel_hi:[1,0]
	v_mul_f32_e32 v100, 0xbfb8aa3b, v100
	v_mul_f32_e32 v101, 0xbfb8aa3b, v101
	v_rcp_f32_e32 v126, v125
	s_nop 0
	v_mul_f32_e32 v125, 1.0, v126
	v_exp_f32_e32 v100, v100
	v_exp_f32_e32 v101, v101
	v_mul_f32_e32 v92, 0xbfb8aa3b, v92
	v_rcp_f32_e32 v126, v124
	s_nop 0
	v_mul_f32_e32 v124, 1.0, v126
	v_pk_mul_f32 v[122:123], v[122:123], v[124:125]
	v_pk_add_f32 v[100:101], v[100:101], 1.0 op_sel_hi:[1,0]
	v_cvt_pk_bf16_f32 v121, v122, v123
	v_mul_f32_e32 v93, 0xbfb8aa3b, v93
	v_exp_f32_e32 v92, v92
	v_exp_f32_e32 v93, v93
	v_rcp_f32_e32 v122, v117
	s_nop 0
	v_mul_f32_e32 v117, 1.0, v122
	v_pk_add_f32 v[92:93], v[92:93], 1.0 op_sel_hi:[1,0]
	v_mul_f32_e32 v84, 0xbfb8aa3b, v84
	v_mul_f32_e32 v85, 0xbfb8aa3b, v85
	v_rcp_f32_e32 v122, v116
	s_nop 0
	v_mul_f32_e32 v116, 1.0, v122
	v_pk_mul_f32 v[112:113], v[112:113], v[116:117]
	v_mul_f32_e32 v116, 0xbfb8aa3b, v118
	v_mul_f32_e32 v117, 0xbfb8aa3b, v119
	v_exp_f32_e32 v116, v116
	v_exp_f32_e32 v117, v117
	v_exp_f32_e32 v84, v84
	v_exp_f32_e32 v85, v85
	v_mul_f32_e32 v76, 0xbfb8aa3b, v76
	v_pk_add_f32 v[116:117], v[116:117], 1.0 op_sel_hi:[1,0]
	v_mul_f32_e32 v77, 0xbfb8aa3b, v77
	v_pk_add_f32 v[84:85], v[84:85], 1.0 op_sel_hi:[1,0]
	v_exp_f32_e32 v76, v76
	v_exp_f32_e32 v77, v77
	v_rcp_f32_e32 v118, v117
	s_nop 0
	v_mul_f32_e32 v117, 1.0, v118
	v_pk_add_f32 v[76:77], v[76:77], 1.0 op_sel_hi:[1,0]
	v_mul_f32_e32 v68, 0xbfb8aa3b, v68
	v_mul_f32_e32 v69, 0xbfb8aa3b, v69
	v_rcp_f32_e32 v118, v116
	s_nop 0
	v_mul_f32_e32 v116, 1.0, v118
	v_cvt_pk_bf16_f32 v122, v112, v113
	v_lshl_add_u32 v112, s33, 8, v140
	v_pk_mul_f32 v[114:115], v[114:115], v[116:117]
	v_ashrrev_i32_e32 v113, 31, v112
	v_cvt_pk_bf16_f32 v123, v114, v115
	v_lshlrev_b64 v[114:115], 11, v[112:113]
	v_lshl_add_u64 v[114:115], s[0:1], 0, v[114:115]
	v_lshl_add_u64 v[114:115], v[114:115], 0, s[4:5]
	v_lshl_add_u64 v[114:115], v[114:115], 0, s[84:85]
	v_lshl_add_u64 v[114:115], v[114:115], 0, v[144:145]
	global_store_dwordx4 v[114:115], v[120:123], off sc1
	v_exp_f32_e32 v68, v68
	v_exp_f32_e32 v69, v69
	v_mul_f32_e32 v60, 0xbfb8aa3b, v60
	v_rcp_f32_e32 v113, v109
	s_nop 0
	v_mul_f32_e32 v109, 1.0, v113
	v_pk_add_f32 v[68:69], v[68:69], 1.0 op_sel_hi:[1,0]
	v_mul_f32_e32 v61, 0xbfb8aa3b, v61
	v_exp_f32_e32 v60, v60
	v_rcp_f32_e32 v113, v108
	s_nop 0
	v_mul_f32_e32 v108, 1.0, v113
	v_pk_mul_f32 v[104:105], v[104:105], v[108:109]
	v_mul_f32_e32 v108, 0xbfb8aa3b, v110
	v_mul_f32_e32 v109, 0xbfb8aa3b, v111
	v_exp_f32_e32 v108, v108
	v_exp_f32_e32 v109, v109
	v_cvt_pk_bf16_f32 v104, v104, v105
	v_exp_f32_e32 v61, v61
	v_mul_f32_e32 v52, 0xbfb8aa3b, v52
	v_pk_add_f32 v[108:109], v[108:109], 1.0 op_sel_hi:[1,0]
	v_mul_f32_e32 v53, 0xbfb8aa3b, v53
	v_pk_add_f32 v[60:61], v[60:61], 1.0 op_sel_hi:[1,0]
	v_exp_f32_e32 v52, v52
	v_exp_f32_e32 v53, v53
	v_rcp_f32_e32 v110, v109
	s_nop 0
	v_mul_f32_e32 v109, 1.0, v110
	v_pk_add_f32 v[52:53], v[52:53], 1.0 op_sel_hi:[1,0]
	v_mul_f32_e32 v44, 0xbfb8aa3b, v44
	v_mul_f32_e32 v45, 0xbfb8aa3b, v45
	v_rcp_f32_e32 v110, v108
	s_nop 0
	v_mul_f32_e32 v108, 1.0, v110
	v_pk_mul_f32 v[106:107], v[106:107], v[108:109]
	v_exp_f32_e32 v44, v44
	v_cvt_pk_bf16_f32 v105, v106, v107
	v_exp_f32_e32 v45, v45
	v_mul_f32_e32 v36, 0xbfb8aa3b, v36
	v_mul_f32_e32 v37, 0xbfb8aa3b, v37
	v_rcp_f32_e32 v106, v101
	s_nop 0
	v_mul_f32_e32 v101, 1.0, v106
	v_pk_add_f32 v[44:45], v[44:45], 1.0 op_sel_hi:[1,0]
	v_exp_f32_e32 v36, v36
	v_exp_f32_e32 v37, v37
	v_rcp_f32_e32 v106, v100
	s_nop 0
	v_mul_f32_e32 v100, 1.0, v106
	v_pk_mul_f32 v[96:97], v[96:97], v[100:101]
	v_mul_f32_e32 v100, 0xbfb8aa3b, v102
	v_mul_f32_e32 v101, 0xbfb8aa3b, v103
	v_exp_f32_e32 v100, v100
	v_exp_f32_e32 v101, v101
	v_pk_add_f32 v[36:37], v[36:37], 1.0 op_sel_hi:[1,0]
	v_mul_f32_e32 v28, 0xbfb8aa3b, v28
	v_mul_f32_e32 v29, 0xbfb8aa3b, v29
	v_pk_add_f32 v[100:101], v[100:101], 1.0 op_sel_hi:[1,0]
	v_exp_f32_e32 v28, v28
	v_exp_f32_e32 v29, v29
	v_mul_f32_e32 v20, 0xbfb8aa3b, v20
	v_mul_f32_e32 v21, 0xbfb8aa3b, v21
	v_rcp_f32_e32 v102, v101
	s_nop 0
	v_mul_f32_e32 v101, 1.0, v102
	v_pk_add_f32 v[28:29], v[28:29], 1.0 op_sel_hi:[1,0]
	v_exp_f32_e32 v20, v20
	v_exp_f32_e32 v21, v21
	v_cvt_pk_bf16_f32 v106, v96, v97
	v_add_u32_e32 v96, 16, v112
	v_ashrrev_i32_e32 v97, 31, v96
	v_lshlrev_b64 v[96:97], 11, v[96:97]
	v_lshl_add_u64 v[96:97], s[0:1], 0, v[96:97]
	v_rcp_f32_e32 v102, v100
	s_nop 0
	v_mul_f32_e32 v100, 1.0, v102
	v_lshl_add_u64 v[96:97], v[96:97], 0, s[4:5]
	v_pk_mul_f32 v[98:99], v[98:99], v[100:101]
	v_lshl_add_u64 v[96:97], v[96:97], 0, s[84:85]
	v_cvt_pk_bf16_f32 v107, v98, v99
	v_lshl_add_u64 v[96:97], v[96:97], 0, v[144:145]
	global_store_dwordx4 v[96:97], v[104:107], off sc1
	v_pk_add_f32 v[20:21], v[20:21], 1.0 op_sel_hi:[1,0]
	v_mul_f32_e32 v12, 0xbfb8aa3b, v12
	v_mul_f32_e32 v13, 0xbfb8aa3b, v13
	v_rcp_f32_e32 v96, v93
	s_nop 0
	v_mul_f32_e32 v93, 1.0, v96
	v_exp_f32_e32 v12, v12
	v_exp_f32_e32 v13, v13
	v_mul_f32_e32 v4, 0xbfb8aa3b, v4
	v_rcp_f32_e32 v96, v92
	s_nop 0
	v_mul_f32_e32 v92, 1.0, v96
	v_pk_mul_f32 v[88:89], v[88:89], v[92:93]
	v_mul_f32_e32 v92, 0xbfb8aa3b, v94
	v_mul_f32_e32 v93, 0xbfb8aa3b, v95
	v_exp_f32_e32 v92, v92
	v_exp_f32_e32 v93, v93
	v_cvt_pk_bf16_f32 v88, v88, v89
	v_pk_add_f32 v[12:13], v[12:13], 1.0 op_sel_hi:[1,0]
	v_mul_f32_e32 v5, 0xbfb8aa3b, v5
	v_pk_add_f32 v[92:93], v[92:93], 1.0 op_sel_hi:[1,0]
	v_exp_f32_e32 v4, v4
	v_exp_f32_e32 v5, v5
	v_rcp_f32_e32 v94, v93
	s_nop 0
	v_mul_f32_e32 v93, 1.0, v94
	v_pk_add_f32 v[4:5], v[4:5], 1.0 op_sel_hi:[1,0]
	v_rcp_f32_e32 v94, v92
	s_nop 0
	v_mul_f32_e32 v92, 1.0, v94
	v_pk_mul_f32 v[90:91], v[90:91], v[92:93]
	s_nop 0
	v_cvt_pk_bf16_f32 v89, v90, v91
	v_rcp_f32_e32 v90, v85
	s_nop 0
	v_mul_f32_e32 v85, 1.0, v90
	v_rcp_f32_e32 v90, v84
	s_nop 0
	v_mul_f32_e32 v84, 1.0, v90
	v_pk_mul_f32 v[80:81], v[80:81], v[84:85]
	v_mul_f32_e32 v84, 0xbfb8aa3b, v86
	v_mul_f32_e32 v85, 0xbfb8aa3b, v87
	v_exp_f32_e32 v84, v84
	v_exp_f32_e32 v85, v85
	s_nop 0
	v_pk_add_f32 v[84:85], v[84:85], 1.0 op_sel_hi:[1,0]
	s_nop 0
	v_rcp_f32_e32 v86, v85
	s_nop 0
	v_mul_f32_e32 v85, 1.0, v86
	v_cvt_pk_bf16_f32 v90, v80, v81
	v_add_u32_e32 v80, 32, v112
	v_ashrrev_i32_e32 v81, 31, v80
	v_lshlrev_b64 v[80:81], 11, v[80:81]
	v_lshl_add_u64 v[80:81], s[0:1], 0, v[80:81]
	v_rcp_f32_e32 v86, v84
	s_nop 0
	v_mul_f32_e32 v84, 1.0, v86
	v_lshl_add_u64 v[80:81], v[80:81], 0, s[4:5]
	v_pk_mul_f32 v[82:83], v[82:83], v[84:85]
	v_lshl_add_u64 v[80:81], v[80:81], 0, s[84:85]
	v_cvt_pk_bf16_f32 v91, v82, v83
	v_lshl_add_u64 v[80:81], v[80:81], 0, v[144:145]
	global_store_dwordx4 v[80:81], v[88:91], off sc1
	v_rcp_f32_e32 v80, v77
	s_nop 0
	v_mul_f32_e32 v77, 1.0, v80
	v_rcp_f32_e32 v80, v76
	s_nop 0
	v_mul_f32_e32 v76, 1.0, v80
	v_pk_mul_f32 v[72:73], v[72:73], v[76:77]
	v_mul_f32_e32 v76, 0xbfb8aa3b, v78
	v_mul_f32_e32 v77, 0xbfb8aa3b, v79
	v_exp_f32_e32 v76, v76
	v_exp_f32_e32 v77, v77
	v_cvt_pk_bf16_f32 v72, v72, v73
	v_pk_add_f32 v[76:77], v[76:77], 1.0 op_sel_hi:[1,0]
	s_nop 0
	v_rcp_f32_e32 v78, v77
	s_nop 0
	v_mul_f32_e32 v77, 1.0, v78
	v_rcp_f32_e32 v78, v76
	s_nop 0
	v_mul_f32_e32 v76, 1.0, v78
	v_pk_mul_f32 v[74:75], v[74:75], v[76:77]
	s_nop 0
	v_cvt_pk_bf16_f32 v73, v74, v75
	v_rcp_f32_e32 v74, v69
	s_nop 0
	v_mul_f32_e32 v69, 1.0, v74
	v_rcp_f32_e32 v74, v68
	s_nop 0
	v_mul_f32_e32 v68, 1.0, v74
	v_pk_mul_f32 v[64:65], v[64:65], v[68:69]
	v_mul_f32_e32 v68, 0xbfb8aa3b, v70
	v_mul_f32_e32 v69, 0xbfb8aa3b, v71
	v_exp_f32_e32 v68, v68
	v_exp_f32_e32 v69, v69
	s_nop 0
	v_pk_add_f32 v[68:69], v[68:69], 1.0 op_sel_hi:[1,0]
	s_nop 0
	v_rcp_f32_e32 v70, v69
	s_nop 0
	v_mul_f32_e32 v69, 1.0, v70
	v_cvt_pk_bf16_f32 v74, v64, v65
	v_add_u32_e32 v64, 48, v112
	v_ashrrev_i32_e32 v65, 31, v64
	v_lshlrev_b64 v[64:65], 11, v[64:65]
	v_lshl_add_u64 v[64:65], s[0:1], 0, v[64:65]
	v_rcp_f32_e32 v70, v68
	s_nop 0
	v_mul_f32_e32 v68, 1.0, v70
	v_lshl_add_u64 v[64:65], v[64:65], 0, s[4:5]
	v_pk_mul_f32 v[66:67], v[66:67], v[68:69]
	v_lshl_add_u64 v[64:65], v[64:65], 0, s[84:85]
	v_cvt_pk_bf16_f32 v75, v66, v67
	v_lshl_add_u64 v[64:65], v[64:65], 0, v[144:145]
	global_store_dwordx4 v[64:65], v[72:75], off sc1
	v_rcp_f32_e32 v64, v61
	s_nop 0
	v_mul_f32_e32 v61, 1.0, v64
	v_rcp_f32_e32 v64, v60
	s_nop 0
	v_mul_f32_e32 v60, 1.0, v64
	v_pk_mul_f32 v[56:57], v[56:57], v[60:61]
	v_mul_f32_e32 v60, 0xbfb8aa3b, v62
	v_mul_f32_e32 v61, 0xbfb8aa3b, v63
	v_exp_f32_e32 v60, v60
	v_exp_f32_e32 v61, v61
	v_cvt_pk_bf16_f32 v56, v56, v57
	v_pk_add_f32 v[60:61], v[60:61], 1.0 op_sel_hi:[1,0]
	s_nop 0
	v_rcp_f32_e32 v62, v61
	s_nop 0
	v_mul_f32_e32 v61, 1.0, v62
	v_rcp_f32_e32 v62, v60
	s_nop 0
	v_mul_f32_e32 v60, 1.0, v62
	v_pk_mul_f32 v[58:59], v[58:59], v[60:61]
	s_nop 0
	v_cvt_pk_bf16_f32 v57, v58, v59
	v_rcp_f32_e32 v58, v53
	s_nop 0
	v_mul_f32_e32 v53, 1.0, v58
	v_rcp_f32_e32 v58, v52
	s_nop 0
	v_mul_f32_e32 v52, 1.0, v58
	v_pk_mul_f32 v[48:49], v[48:49], v[52:53]
	v_mul_f32_e32 v52, 0xbfb8aa3b, v54
	v_mul_f32_e32 v53, 0xbfb8aa3b, v55
	v_exp_f32_e32 v52, v52
	v_exp_f32_e32 v53, v53
	s_nop 0
	v_pk_add_f32 v[52:53], v[52:53], 1.0 op_sel_hi:[1,0]
	s_nop 0
	v_rcp_f32_e32 v54, v53
	s_nop 0
	v_mul_f32_e32 v53, 1.0, v54
	v_cvt_pk_bf16_f32 v58, v48, v49
	v_add_u32_e32 v48, 0x80, v112
	v_ashrrev_i32_e32 v49, 31, v48
	v_lshlrev_b64 v[48:49], 11, v[48:49]
	v_lshl_add_u64 v[48:49], s[0:1], 0, v[48:49]
	v_rcp_f32_e32 v54, v52
	s_nop 0
	v_mul_f32_e32 v52, 1.0, v54
	v_lshl_add_u64 v[48:49], v[48:49], 0, s[4:5]
	v_pk_mul_f32 v[50:51], v[50:51], v[52:53]
	v_lshl_add_u64 v[48:49], v[48:49], 0, s[84:85]
	v_cvt_pk_bf16_f32 v59, v50, v51
	v_lshl_add_u64 v[48:49], v[48:49], 0, v[144:145]
	global_store_dwordx4 v[48:49], v[56:59], off sc1
	v_rcp_f32_e32 v48, v45
	s_nop 0
	v_mul_f32_e32 v45, 1.0, v48
	v_rcp_f32_e32 v48, v44
	s_nop 0
	v_mul_f32_e32 v44, 1.0, v48
	v_pk_mul_f32 v[40:41], v[40:41], v[44:45]
	v_mul_f32_e32 v44, 0xbfb8aa3b, v46
	v_mul_f32_e32 v45, 0xbfb8aa3b, v47
	v_exp_f32_e32 v44, v44
	v_exp_f32_e32 v45, v45
	v_cvt_pk_bf16_f32 v40, v40, v41
	v_pk_add_f32 v[44:45], v[44:45], 1.0 op_sel_hi:[1,0]
	s_nop 0
	v_rcp_f32_e32 v46, v45
	s_nop 0
	v_mul_f32_e32 v45, 1.0, v46
	v_rcp_f32_e32 v46, v44
	s_nop 0
	v_mul_f32_e32 v44, 1.0, v46
	v_pk_mul_f32 v[42:43], v[42:43], v[44:45]
	s_nop 0
	v_cvt_pk_bf16_f32 v41, v42, v43
	v_rcp_f32_e32 v42, v37
	s_nop 0
	v_mul_f32_e32 v37, 1.0, v42
	v_rcp_f32_e32 v42, v36
	s_nop 0
	v_mul_f32_e32 v36, 1.0, v42
	v_pk_mul_f32 v[32:33], v[32:33], v[36:37]
	v_mul_f32_e32 v36, 0xbfb8aa3b, v38
	v_mul_f32_e32 v37, 0xbfb8aa3b, v39
	v_exp_f32_e32 v36, v36
	v_exp_f32_e32 v37, v37
	s_nop 0
	v_pk_add_f32 v[36:37], v[36:37], 1.0 op_sel_hi:[1,0]
	s_nop 0
	v_rcp_f32_e32 v38, v37
	s_nop 0
	v_mul_f32_e32 v37, 1.0, v38
	v_cvt_pk_bf16_f32 v42, v32, v33
	v_add_u32_e32 v32, 0x90, v112
	v_ashrrev_i32_e32 v33, 31, v32
	v_lshlrev_b64 v[32:33], 11, v[32:33]
	v_lshl_add_u64 v[32:33], s[0:1], 0, v[32:33]
	v_rcp_f32_e32 v38, v36
	s_nop 0
	v_mul_f32_e32 v36, 1.0, v38
	v_lshl_add_u64 v[32:33], v[32:33], 0, s[4:5]
	v_pk_mul_f32 v[34:35], v[34:35], v[36:37]
	v_lshl_add_u64 v[32:33], v[32:33], 0, s[84:85]
	v_cvt_pk_bf16_f32 v43, v34, v35
	v_lshl_add_u64 v[32:33], v[32:33], 0, v[144:145]
	global_store_dwordx4 v[32:33], v[40:43], off sc1
	v_rcp_f32_e32 v32, v29
	s_nop 0
	v_mul_f32_e32 v29, 1.0, v32
	v_rcp_f32_e32 v32, v28
	s_nop 0
	v_mul_f32_e32 v28, 1.0, v32
	v_pk_mul_f32 v[24:25], v[24:25], v[28:29]
	v_mul_f32_e32 v28, 0xbfb8aa3b, v30
	v_mul_f32_e32 v29, 0xbfb8aa3b, v31
	v_exp_f32_e32 v28, v28
	v_exp_f32_e32 v29, v29
	v_cvt_pk_bf16_f32 v24, v24, v25
	v_pk_add_f32 v[28:29], v[28:29], 1.0 op_sel_hi:[1,0]
	s_nop 0
	v_rcp_f32_e32 v30, v29
	s_nop 0
	v_mul_f32_e32 v29, 1.0, v30
	v_rcp_f32_e32 v30, v28
	s_nop 0
	v_mul_f32_e32 v28, 1.0, v30
	v_pk_mul_f32 v[26:27], v[26:27], v[28:29]
	s_nop 0
	v_cvt_pk_bf16_f32 v25, v26, v27
	v_rcp_f32_e32 v26, v21
	s_nop 0
	v_mul_f32_e32 v21, 1.0, v26
	v_rcp_f32_e32 v26, v20
	s_nop 0
	v_mul_f32_e32 v20, 1.0, v26
	v_pk_mul_f32 v[16:17], v[16:17], v[20:21]
	v_mul_f32_e32 v20, 0xbfb8aa3b, v22
	v_mul_f32_e32 v21, 0xbfb8aa3b, v23
	v_exp_f32_e32 v20, v20
	v_exp_f32_e32 v21, v21
	s_nop 0
	v_pk_add_f32 v[20:21], v[20:21], 1.0 op_sel_hi:[1,0]
	s_nop 0
	v_rcp_f32_e32 v22, v21
	s_nop 0
	v_mul_f32_e32 v21, 1.0, v22
	v_cvt_pk_bf16_f32 v26, v16, v17
	v_add_u32_e32 v16, 0xa0, v112
	v_ashrrev_i32_e32 v17, 31, v16
	v_lshlrev_b64 v[16:17], 11, v[16:17]
	v_lshl_add_u64 v[16:17], s[0:1], 0, v[16:17]
	v_rcp_f32_e32 v22, v20
	s_nop 0
	v_mul_f32_e32 v20, 1.0, v22
	v_lshl_add_u64 v[16:17], v[16:17], 0, s[4:5]
	v_pk_mul_f32 v[18:19], v[18:19], v[20:21]
	v_lshl_add_u64 v[16:17], v[16:17], 0, s[84:85]
	v_cvt_pk_bf16_f32 v27, v18, v19
	v_lshl_add_u64 v[16:17], v[16:17], 0, v[144:145]
	global_store_dwordx4 v[16:17], v[24:27], off sc1
	v_rcp_f32_e32 v16, v13
	s_nop 0
	v_mul_f32_e32 v13, 1.0, v16
	v_rcp_f32_e32 v16, v12
	s_nop 0
	v_mul_f32_e32 v12, 1.0, v16
	v_pk_mul_f32 v[8:9], v[8:9], v[12:13]
	v_mul_f32_e32 v12, 0xbfb8aa3b, v14
	v_mul_f32_e32 v13, 0xbfb8aa3b, v15
	v_exp_f32_e32 v12, v12
	v_exp_f32_e32 v13, v13
	v_cvt_pk_bf16_f32 v8, v8, v9
	v_pk_add_f32 v[12:13], v[12:13], 1.0 op_sel_hi:[1,0]
	s_nop 0
	v_rcp_f32_e32 v14, v13
	s_nop 0
	v_mul_f32_e32 v13, 1.0, v14
	v_rcp_f32_e32 v14, v12
	s_nop 0
	v_mul_f32_e32 v12, 1.0, v14
	v_pk_mul_f32 v[10:11], v[10:11], v[12:13]
	s_nop 0
	v_cvt_pk_bf16_f32 v9, v10, v11
	v_rcp_f32_e32 v10, v5
	s_nop 0
	v_mul_f32_e32 v5, 1.0, v10
	v_rcp_f32_e32 v10, v4
	s_nop 0
	v_mul_f32_e32 v4, 1.0, v10
	v_pk_mul_f32 v[0:1], v[0:1], v[4:5]
	v_mul_f32_e32 v4, 0xbfb8aa3b, v6
	v_mul_f32_e32 v5, 0xbfb8aa3b, v7
	v_exp_f32_e32 v4, v4
	v_exp_f32_e32 v5, v5
	s_nop 0
	v_pk_add_f32 v[4:5], v[4:5], 1.0 op_sel_hi:[1,0]
	s_nop 0
	v_rcp_f32_e32 v6, v5
	s_nop 0
	v_mul_f32_e32 v5, 1.0, v6
	v_cvt_pk_bf16_f32 v10, v0, v1
	v_add_u32_e32 v0, 0xb0, v112
	v_ashrrev_i32_e32 v1, 31, v0
	v_lshlrev_b64 v[0:1], 11, v[0:1]
	v_lshl_add_u64 v[0:1], s[0:1], 0, v[0:1]
	v_rcp_f32_e32 v6, v4
	s_nop 0
	v_mul_f32_e32 v4, 1.0, v6
	v_lshl_add_u64 v[0:1], v[0:1], 0, s[4:5]
	v_pk_mul_f32 v[2:3], v[2:3], v[4:5]
	v_lshl_add_u64 v[0:1], v[0:1], 0, s[84:85]
	v_cvt_pk_bf16_f32 v11, v2, v3
	v_lshl_add_u64 v[0:1], v[0:1], 0, v[144:145]
	global_store_dwordx4 v[0:1], v[8:11], off sc1
	s_load_dword s4, s[80:81], 0x0
	s_waitcnt lgkmcnt(0)
	s_add_i32 s30, s4, s30
	s_cmpk_gt_i32 s30, 0xff
	s_cbranch_scc1 .LBB0_680

.LBB0_1498:
	s_mov_b32 s4, 0x18e18e0
	s_lshr_b32 s4, s4, s54
	s_bitcmp1_b32 s4, 0
	s_cbranch_scc0 .Lgs_grid
	v_readlane_b32 s4, v254, 0
	s_and_b32 s5, s4, 31
	s_lshr_b32 s4, s4, 5
	s_lshl_b32 s24, s5, 3
	s_add_i32 s24, s24, s4
	s_lshl_b32 s24, s24, 2
	s_add_u32 s28, s52, 0x3600
	s_addc_u32 s29, s53, 0
	v_mov_b32_e32 v0, s24
	v_mov_b32_e32 v1, s54
	global_store_dword v0, v1, s[28:29] sc1
	buffer_inv sc1
	s_lshl_b32 s24, s5, 5
	v_mov_b32_e32 v0, s24
	s_mov_b32 s33, 0
